# recurrence phase: scan-role waves of the prompt items run at s_setprio 2 (prep waves share their SIMDs)
# baseline (speedup 1.0000x reference)
; #define GLA_BAR() do { asm volatile("s_waitcnt lgkmcnt(0)" ::: "memory"); __builtin_amdgcn_s_barrier(); asm volatile("" ::: "memory"); } while (0)
; __device__ __forceinline__ void run(unsigned char* ws, const float* s0  , float* sout, const float* gon, int row0, int h, int nch, char* lds, int wave, int lane) {
;     ...
;     if (scan) {
;         if (s0) { const unsigned sl = (unsigned)((4 * hi) * HI + 32 * vq + r32) * 4u;
; #pragma unroll
;             for (int kt = 0; kt < 4; ++kt)
; #pragma unroll
;                 for (int r = 0; r < 16; ++r) S[kt][r] = *(const float*)((const char*)s0 + sl + (unsigned)((32 * kt + (r & 3) + 8 * (r >> 2)) * HI * 4));
;         } else {
; #pragma unroll
;             for (int kt = 0; kt < 4; ++kt) S[kt] = f32x16{};
;         }
;         GLA_BAR();
.LBB0_367:
	s_setprio 0
	s_waitcnt lgkmcnt(0)
	s_barrier

; #define GLA_BAR() do { asm volatile("s_waitcnt lgkmcnt(0)" ::: "memory"); __builtin_amdgcn_s_barrier(); asm volatile("" ::: "memory"); } while (0)
; __device__ __forceinline__ void run(unsigned char* ws, const float* s0  , float* sout, const float* gon, int row0, int h, int nch, char* lds, int wave, int lane) {
;     ...
;     const bf16_t* FGp = (const bf16_t*)(ws + WS_FG) + (size_t)row0 * 2048 + h * 128;
;     const bf16_t* QSp = (const bf16_t*)(ws + WS_QSIL) + (size_t)row0 * 2048 + h * 128;
;     const bf16_t* VBp = (const bf16_t*)(ws + WS_VB) + (size_t)row0 * 2048 + h * 128;
;     const bf16_t* GSp = (const bf16_t*)(ws + WS_GS) + (size_t)row0 * 2048 + h * 128;
;     bf16_t* YCp = (bf16_t*)(ws + WS_YCAT) + (size_t)row0 * DM + h * 128;
;     ...
;         if (s0) { const unsigned sl = (unsigned)((4 * hi) * HI + 32 * vq + r32) * 4u;
; #pragma unroll
;             for (int kt = 0; kt < 4; ++kt)
; #pragma unroll
;                 for (int r = 0; r < 16; ++r) S[kt][r] = *(const float*)((const char*)s0 + sl + (unsigned)((32 * kt + (r & 3) + 8 * (r >> 2)) * HI * 4));
;         } else {
; #pragma unroll
;             for (int kt = 0; kt < 4; ++kt) S[kt] = f32x16{};
;         }
;         GLA_BAR();
; #pragma unroll
;         for (int g = 0; g < 4; ++g) gnr[g] = *(const f32x4*)(gonL + 32 * vq + 8 * g + 4 * hi);
.LBB0_439:
	s_and_b64 vcc, exec, s[2:3]
	s_cbranch_vccz .LBB0_367
	s_setprio 2
	s_lshl_b64 s[2:3], s[80:81], 1
	v_readlane_b32 s48, v255, 36
	s_add_u32 s48, s48, s2
	v_readlane_b32 s49, v255, 53
	s_addc_u32 s49, s49, s3
	s_lshl_b32 s52, s52, 1
	s_add_u32 s48, s48, s52
	s_addc_u32 s49, s49, 0
	v_readlane_b32 s54, v255, 51
	s_waitcnt lgkmcnt(0)
	s_barrier
	s_add_u32 s2, s54, s2
	v_readlane_b32 s54, v255, 52
	ds_read_b128 v[110:113], v152
	ds_read_b128 v[106:109], v152 offset:32
	ds_read_b128 v[102:105], v152 offset:64
	ds_read_b128 v[98:101], v152 offset:96
	s_addc_u32 s3, s54, s3
	s_add_u32 s2, s2, s52
	v_readlane_b32 s52, v255, 32
	s_addc_u32 s3, s3, 0
	s_lshl_b32 s52, s52, 1
	s_add_u32 s2, s2, s52
	s_addc_u32 s3, s3, 0
	s_waitcnt vmcnt(0)
	v_mov_b32_e32 v34, 0
	v_lshl_add_u64 v[130:131], v[116:117], 1, s[2:3]
	v_lshl_add_u64 v[132:133], v[124:125], 1, s[48:49]
	s_mov_b32 s52, 0
	v_mov_b32_e32 v134, 0
	v_mov_b32_e32 v135, 0
	v_mov_b32_e32 v128, 0
	v_mov_b32_e32 v129, 0
	v_mov_b32_e32 v126, 0
	v_mov_b32_e32 v127, 0
	v_mov_b32_e32 v114, 0
	v_mov_b32_e32 v115, 0
	s_mov_b32 s54, 0
	v_mov_b32_e32 v35, v34
	v_mov_b32_e32 v36, v34
	v_mov_b32_e32 v37, v34
	v_mov_b32_e32 v38, v34
	v_mov_b32_e32 v39, v34
	v_mov_b32_e32 v40, v34
	v_mov_b32_e32 v41, v34
	v_mov_b32_e32 v42, v34
	v_mov_b32_e32 v43, v34
	v_mov_b32_e32 v44, v34
	v_mov_b32_e32 v45, v34
	v_mov_b32_e32 v46, v34
	v_mov_b32_e32 v47, v34
	v_mov_b32_e32 v48, v34
	v_mov_b32_e32 v49, v34
	v_mov_b32_e32 v50, v34
	v_mov_b32_e32 v51, v34
	v_mov_b32_e32 v52, v34
	v_mov_b32_e32 v53, v34
	v_mov_b32_e32 v54, v34
	v_mov_b32_e32 v55, v34
	v_mov_b32_e32 v56, v34
	v_mov_b32_e32 v57, v34
	v_mov_b32_e32 v58, v34
	v_mov_b32_e32 v59, v34
	v_mov_b32_e32 v60, v34
	v_mov_b32_e32 v61, v34
	v_mov_b32_e32 v62, v34
	v_mov_b32_e32 v63, v34
	v_mov_b32_e32 v64, v34
	v_mov_b32_e32 v65, v34
	v_mov_b32_e32 v18, v34
	v_mov_b32_e32 v19, v34
	v_mov_b32_e32 v20, v34
	v_mov_b32_e32 v21, v34
	v_mov_b32_e32 v22, v34
	v_mov_b32_e32 v23, v34
	v_mov_b32_e32 v24, v34
	v_mov_b32_e32 v25, v34
	v_mov_b32_e32 v26, v34
	v_mov_b32_e32 v27, v34
	v_mov_b32_e32 v28, v34
	v_mov_b32_e32 v29, v34
	v_mov_b32_e32 v30, v34
	v_mov_b32_e32 v31, v34
	v_mov_b32_e32 v32, v34
	v_mov_b32_e32 v33, v34
	v_mov_b32_e32 v2, v34
	v_mov_b32_e32 v3, v34
	v_mov_b32_e32 v4, v34
	v_mov_b32_e32 v5, v34
	v_mov_b32_e32 v6, v34
	v_mov_b32_e32 v7, v34
	v_mov_b32_e32 v8, v34
	v_mov_b32_e32 v9, v34
	v_mov_b32_e32 v10, v34
	v_mov_b32_e32 v11, v34
	v_mov_b32_e32 v12, v34
	v_mov_b32_e32 v13, v34
	v_mov_b32_e32 v14, v34
	v_mov_b32_e32 v15, v34
	v_mov_b32_e32 v16, v34
	v_mov_b32_e32 v17, v34
	v_mov_b32_e32 v66, v34
	v_mov_b32_e32 v67, v34
	v_mov_b32_e32 v68, v34
	v_mov_b32_e32 v69, v34
	v_mov_b32_e32 v70, v34
	v_mov_b32_e32 v71, v34
	v_mov_b32_e32 v72, v34
	v_mov_b32_e32 v73, v34
	v_mov_b32_e32 v74, v34
	v_mov_b32_e32 v75, v34
	v_mov_b32_e32 v76, v34
	v_mov_b32_e32 v77, v34
	v_mov_b32_e32 v78, v34
	v_mov_b32_e32 v79, v34
	v_mov_b32_e32 v80, v34
	v_mov_b32_e32 v81, v34
	s_branch .LBB0_442
